# attention: K ring 4 / V ring 6 prefetch distance 3, V fragment ds_reads moved from load segment into QK MFMA shadow
# speedup vs baseline: 1.0135x; 1.0135x over previous
; #define LAS __attribute__((address_space(3)))
; template <int MODE> __device__ __forceinline__ void attn_unit(const bf16_t* __restrict__ Q, const bf16_t* __restrict__ KV, const bf16_t* __restrict__ KR, bf16_t* __restrict__ O,
;                                           long rowbase, int q0, int h, LAS char* lds) {
;   const int tid = threadIdx.x, lane = tid & 63, r32 = lane & 31, hi = lane >> 5; const int wid = __builtin_amdgcn_readfirstlane(tid >> 6);
;   LAS char* Kl = lds + LDS_K; LAS char* Vl = lds + LDS_V;
;   LAS float* ws = (LAS float*)(lds + LDS_WS) + wid * 64; LAS float* li_l = ws; LAS float* al_l = ws + 32;
;   const bf16_t* Kw = KV + (rowbase + lane) * LDKV + h * 128 + wid * 8;
;   const bf16_t* KRw = KR + (rowbase + lane) * LDKR + (wid & 3) * 8;
;   const bf16_t* Vw = KV + (rowbase + 16 * (wid & 3) + (lane >> 2)) * LDKV + h * 128 + 64 + (wid >> 2) * 32 + (lane & 3) * 8;
;     ...
;   float m_reg = -1e30f, l_reg = 0; f32x16 o[2] = {}; bf16x8 qr[6];
;   const bf16_t* Qw = Q + (rowbase + q0 + wid * QBLK + r32) * LDQ + h * QKD + hi * 8;
; #pragma unroll
;   for (int d0 = 0; d0 < 6; ++d0) qr[d0] = *reinterpret_cast<const bf16x8*>(Qw + d0 * 16);
;   asm volatile("" ::: "memory");
;   ISSUE(0, 0, 0); ISSUE(1, KSLOT, VSLOT);
;   const int vbase = (int)(unsigned)(uintptr_t)Vl + ((lane >> 4) & 1) * 32 + (lane & 3) * 8 + (4 * hi + ((lane & 15) >> 2)) * 64;
;   f32x16 pA0, pA1, pB0, pB1; float mnA, mnB, alA, alB; bf16x8 pa0, pa1, pa2, pa3; constexpr int NT = SEQ / KVBLK;
;   int kprev = 2 * KSLOT, kcur = 0, knext = KSLOT;
;     ...
;   if (hi == 0) li_l[r32] = l_reg; asm volatile("s_waitcnt lgkmcnt(0)" ::: "memory");
;   float rli[16];
; #pragma unroll
;   for (int r = 0; r < 16; ++r) rli[r] = __builtin_amdgcn_rcpf(li_l[crow(r, hi)]);
;   bf16_t* Ow = O + (rowbase + q0 + wid * QBLK) * LDO + h * VD;
;   {
;     LAS bf16_t* stg = (LAS bf16_t*)(lds + LDS_OST) + wid * 2048;
; #pragma unroll
;     for (int r = 0; r < 16; ++r) { const int orow = crow(r, hi);
; #pragma unroll
;       for (int d0 = 0; d0 < 2; ++d0) stg[orow * 64 + d0 * 32 + r32] = (bf16_t)(cvt_pk_bf16(o[d0][r] * rli[r], 0.f) & 0xffffu); }
;     asm volatile("s_waitcnt lgkmcnt(0)" ::: "memory");
; #pragma unroll
;     for (int i = 0; i < 4; ++i) { const int row = i * 8 + (lane >> 3), ch = lane & 7; const u32x4 v = *(const LAS u32x4*)(stg + row * 64 + ch * 8); *(u32x4*)(Ow + (long)row * LDO + ch * 8) = v; }
;   }
.LBB0_550:
	s_cmp_lt_i32 s30, 4
	s_cselect_b64 s[2:3], -1, 0
	s_and_b64 s[0:1], s[2:3], s[0:1]
	s_cmpk_lt_i32 s22, 0xa00
	s_cselect_b64 s[2:3], -1, 0
	s_and_b64 s[2:3], s[0:1], s[2:3]
	s_andn2_b64 vcc, exec, s[2:3]
	s_cbranch_vccnz .LBB0_606
	v_lshlrev_b32_e32 v3, 3, v195
	v_lshlrev_b32_e32 v4, 1, v195
	v_lshrrev_b32_e32 v1, 5, v194
	v_and_b32_e32 v0, 24, v3
	v_and_b32_e32 v4, 32, v4
	v_lshlrev_b32_e32 v6, 4, v195
	s_add_i32 s2, 0, 0xc000
	v_lshlrev_b32_e32 v2, 3, v1
	v_lshlrev_b32_e32 v5, 8, v1
	v_and_b32_e32 v6, 0xc0, v6
	v_add3_u32 v4, v4, s2, v0
	v_lshlrev_b32_e32 v203, 10, v1
	v_lshlrev_b32_e32 v232, 4, v1
	v_lshlrev_b32_e32 v235, 9, v1
	v_lshrrev_b32_e32 v1, 3, v194
	v_add3_u32 v197, v4, v6, v5
	v_and_b32_e32 v4, 56, v3
	v_or_b32_e32 v3, 8, v1
	v_and_b32_e32 v192, 31, v195
	v_lshlrev_b32_e32 v236, 7, v1
	v_lshlrev_b32_e32 v6, 10, v1
	v_lshlrev_b32_e32 v237, 7, v3
	v_lshlrev_b32_e32 v8, 10, v3
	v_or_b32_e32 v3, 16, v1
	v_or_b32_e32 v1, 24, v1
	v_mov_b32_e32 v199, 0
	v_lshlrev_b32_e32 v230, 4, v192
	s_waitcnt lgkmcnt(0)
	v_lshlrev_b32_e32 v10, 10, v3
	v_lshlrev_b32_e32 v239, 7, v1
	v_lshlrev_b32_e32 v12, 10, v1
	v_and_b32_e32 v1, 3, v195
	v_lshrrev_b32_e32 v193, 2, v194
	s_mov_b32 s7, 0
	v_add3_u32 v231, 0, v203, v230
	v_cmp_gt_u32_e64 s[2:3], 32, v194
	v_add_u32_e32 v233, 0x4000, v197
	v_add_u32_e32 v234, 0x6000, v197
	v_lshlrev_b32_e32 v238, 7, v3
	v_lshlrev_b32_e32 v200, 6, v194
	v_mov_b32_e32 v201, v199
	v_lshlrev_b32_e32 v202, 4, v1
	v_lshlrev_b32_e32 v204, 11, v194
	v_mov_b32_e32 v205, v199
	v_mov_b32_e32 v240, 0x600
	v_lshlrev_b32_e32 v206, 1, v2
	v_mov_b32_e32 v207, v199
	v_lshlrev_b32_e32 v208, 1, v0
	v_mov_b32_e32 v209, v199
	s_mov_b64 s[8:9], 0x20000
	s_mov_b64 s[10:11], 0x40000
	s_mov_b64 s[12:13], 0x2000
	s_mov_b32 s23, 0x4138aa3b
	s_mov_b64 s[14:15], 0x29c08000
	s_mov_b64 s[16:17], 0x1fc84080
	s_mov_b64 s[18:19], 0x1fca4000
	s_mov_b64 s[24:25], 0x29c09000
	s_mov_b64 s[54:55], 0x1fca4080
	v_lshlrev_b32_e32 v198, 1, v4
	v_lshlrev_b32_e32 v210, 1, v6
	v_lshlrev_b32_e32 v212, 1, v8
	v_lshlrev_b32_e32 v214, 1, v10
	v_lshlrev_b32_e32 v216, 1, v12
	v_mov_b64_e32 v[218:219], s[52:53]
	v_mov_b32_e32 v241, 0xf149f2ca
	s_branch .LBB0_553
.LBB0_552:
	s_or_b64 exec, exec, s[4:5]
	s_waitcnt lgkmcnt(0)
	v_add_u32_e32 v40, s62, v232
	ds_read_b128 v[32:35], v40
	ds_read_b128 v[36:39], v40 offset:32
	s_lshl_b32 s6, s35, 12
	s_add_i32 s6, s6, 0
	s_add_i32 s6, s6, 0x18800
	s_waitcnt lgkmcnt(0)
	v_rcp_f32_e32 v41, v32
	v_rcp_f32_e32 v42, v33
	v_rcp_f32_e32 v43, v34
	v_rcp_f32_e32 v44, v35
	v_rcp_f32_e32 v45, v36
	ds_read_b128 v[32:35], v40 offset:64
	v_rcp_f32_e32 v46, v37
	v_rcp_f32_e32 v47, v38
	v_rcp_f32_e32 v48, v39
	ds_read_b128 v[36:39], v40 offset:96
	v_lshlrev_b32_e32 v40, 1, v192
	v_mul_f32_e32 v0, v0, v41
	v_add3_u32 v40, s6, v235, v40
	v_cvt_pk_bf16_f32 v0, v0, v199
	ds_write_b16 v40, v0
	v_mul_f32_e32 v0, v16, v41
	v_cvt_pk_bf16_f32 v0, v0, v199
	ds_write_b16 v40, v0 offset:64
	v_mul_f32_e32 v0, v1, v42
	v_cvt_pk_bf16_f32 v0, v0, v199
	ds_write_b16 v40, v0 offset:128
	v_mul_f32_e32 v0, v17, v42
	v_cvt_pk_bf16_f32 v0, v0, v199
	ds_write_b16 v40, v0 offset:192
	v_mul_f32_e32 v0, v2, v43
	v_cvt_pk_bf16_f32 v0, v0, v199
	ds_write_b16 v40, v0 offset:256
	v_mul_f32_e32 v0, v18, v43
	v_cvt_pk_bf16_f32 v0, v0, v199
	ds_write_b16 v40, v0 offset:320
	v_mul_f32_e32 v0, v3, v44
	v_cvt_pk_bf16_f32 v0, v0, v199
	ds_write_b16 v40, v0 offset:384
	v_mul_f32_e32 v0, v19, v44
	v_cvt_pk_bf16_f32 v0, v0, v199
	ds_write_b16 v40, v0 offset:448
	v_mul_f32_e32 v0, v4, v45
	v_cvt_pk_bf16_f32 v0, v0, v199
	ds_write_b16 v40, v0 offset:1024
	v_mul_f32_e32 v0, v20, v45
	v_cvt_pk_bf16_f32 v0, v0, v199
	ds_write_b16 v40, v0 offset:1088
	v_mul_f32_e32 v0, v5, v46
	v_cvt_pk_bf16_f32 v0, v0, v199
	ds_write_b16 v40, v0 offset:1152
	v_mul_f32_e32 v0, v21, v46
	v_cvt_pk_bf16_f32 v0, v0, v199
	ds_write_b16 v40, v0 offset:1216
	v_mul_f32_e32 v0, v6, v47
	v_cvt_pk_bf16_f32 v0, v0, v199
	ds_write_b16 v40, v0 offset:1280
	v_mul_f32_e32 v0, v22, v47
	v_cvt_pk_bf16_f32 v0, v0, v199
	s_waitcnt lgkmcnt(0)
	v_rcp_f32_e32 v32, v32
	ds_write_b16 v40, v0 offset:1344
	v_mul_f32_e32 v0, v7, v48
	v_cvt_pk_bf16_f32 v0, v0, v199
	ds_write_b16 v40, v0 offset:1408
	v_mul_f32_e32 v0, v23, v48
	v_cvt_pk_bf16_f32 v0, v0, v199
	v_rcp_f32_e32 v33, v33
	ds_write_b16 v40, v0 offset:1472
	v_mul_f32_e32 v0, v8, v32
	v_cvt_pk_bf16_f32 v0, v0, v199
	ds_write_b16 v40, v0 offset:2048
	v_mul_f32_e32 v0, v24, v32
	v_cvt_pk_bf16_f32 v0, v0, v199
	v_rcp_f32_e32 v34, v34
	ds_write_b16 v40, v0 offset:2112
	v_mul_f32_e32 v0, v9, v33
	v_cvt_pk_bf16_f32 v0, v0, v199
	ds_write_b16 v40, v0 offset:2176
	v_mul_f32_e32 v0, v25, v33
	v_cvt_pk_bf16_f32 v0, v0, v199
	v_rcp_f32_e32 v35, v35
	ds_write_b16 v40, v0 offset:2240
	v_mul_f32_e32 v0, v10, v34
	v_cvt_pk_bf16_f32 v0, v0, v199
	ds_write_b16 v40, v0 offset:2304
	v_mul_f32_e32 v0, v26, v34
	v_cvt_pk_bf16_f32 v0, v0, v199
	v_rcp_f32_e32 v36, v36
	ds_write_b16 v40, v0 offset:2368
	v_mul_f32_e32 v0, v11, v35
	v_cvt_pk_bf16_f32 v0, v0, v199
	ds_write_b16 v40, v0 offset:2432
	v_mul_f32_e32 v0, v27, v35
	v_cvt_pk_bf16_f32 v0, v0, v199
	v_rcp_f32_e32 v37, v37
	ds_write_b16 v40, v0 offset:2496
	v_mul_f32_e32 v0, v12, v36
	v_cvt_pk_bf16_f32 v0, v0, v199
	ds_write_b16 v40, v0 offset:3072
	v_mul_f32_e32 v0, v28, v36
	v_cvt_pk_bf16_f32 v0, v0, v199
	v_rcp_f32_e32 v38, v38
	ds_write_b16 v40, v0 offset:3136
	v_mul_f32_e32 v0, v13, v37
	v_cvt_pk_bf16_f32 v0, v0, v199
	ds_write_b16 v40, v0 offset:3200
	v_mul_f32_e32 v0, v29, v37
	v_cvt_pk_bf16_f32 v0, v0, v199
	v_rcp_f32_e32 v39, v39
	ds_write_b16 v40, v0 offset:3264
	v_mul_f32_e32 v0, v14, v38
	v_cvt_pk_bf16_f32 v0, v0, v199
	ds_write_b16 v40, v0 offset:3328
	v_mul_f32_e32 v0, v30, v38
	v_cvt_pk_bf16_f32 v0, v0, v199
	ds_write_b16 v40, v0 offset:3392
	v_mul_f32_e32 v0, v15, v39
	v_cvt_pk_bf16_f32 v0, v0, v199
	ds_write_b16 v40, v0 offset:3456
	v_mul_f32_e32 v0, v31, v39
	s_lshl_b64 s[4:5], s[52:53], 11
	v_cvt_pk_bf16_f32 v0, v0, v199
	ds_write_b16 v40, v0 offset:3520
	v_add_u32_e32 v12, s6, v198
	s_add_u32 s4, s40, s4
	s_waitcnt lgkmcnt(0)
	v_add_u32_e32 v0, v12, v236
	s_addc_u32 s5, s41, s5
	s_lshl_b32 s34, s34, 7
	ds_read_b128 v[0:3], v0
	v_add_u32_e32 v4, v12, v237
	s_add_u32 s4, s4, s34
	ds_read_b128 v[4:7], v4
	s_addc_u32 s5, s5, 0
	v_lshl_add_u64 v[8:9], s[4:5], 0, v[198:199]
	v_mov_b32_e32 v211, v199
	v_lshl_add_u64 v[10:11], v[8:9], 0, v[210:211]
	v_mov_b32_e32 v213, v199
	s_waitcnt lgkmcnt(0)
	global_store_dwordx4 v[10:11], v[0:3], off
	v_mov_b32_e32 v215, v199
	v_lshl_add_u64 v[10:11], v[8:9], 0, v[214:215]
	v_lshl_add_u64 v[0:1], v[8:9], 0, v[212:213]
	global_store_dwordx4 v[0:1], v[4:7], off
	v_add_u32_e32 v0, v12, v238
	ds_read_b128 v[0:3], v0
	v_add_u32_e32 v4, v12, v239
	ds_read_b128 v[4:7], v4
	v_mov_b32_e32 v217, v199
	s_add_i32 s22, s22, s92
	s_waitcnt lgkmcnt(0)
	global_store_dwordx4 v[10:11], v[0:3], off
	s_cmpk_lt_i32 s22, 0xa00
	s_nop 0
	v_lshl_add_u64 v[0:1], v[8:9], 0, v[216:217]
	global_store_dwordx4 v[0:1], v[4:7], off
	s_waitcnt vmcnt(0) lgkmcnt(0)
	s_barrier
; #define LAS __attribute__((address_space(3)))
; #define ISSUE(t, ks, vs) do { GL(Kw + (long)(t) * KVBLK * LDKV, Kl + (ks) + wid * 1024); if (wid < 4) GL(KRw + (long)(t) * KVBLK * LDKR, Kl + (ks) + (8 + wid) * 1024); \
;     GL(Vw + (long)(t) * KVBLK * LDKV, Vl + (vs) + wid * 1024); } while (0)
; #define VMW_PART() do { if (wid < 4) asm volatile("s_waitcnt vmcnt(3) lgkmcnt(0)" ::: "memory"); else asm volatile("s_waitcnt vmcnt(2) lgkmcnt(0)" ::: "memory"); } while (0)
; #define BAR() do { SBAR(); __builtin_amdgcn_s_barrier(); asm volatile("" ::: "memory"); SBAR(); } while (0)
; template <int MODE> __device__ __forceinline__ void attn_unit(const bf16_t* __restrict__ Q, const bf16_t* __restrict__ KV, const bf16_t* __restrict__ KR, bf16_t* __restrict__ O,
;                                           long rowbase, int q0, int h, LAS char* lds) {
;   const int tid = threadIdx.x, lane = tid & 63, r32 = lane & 31, hi = lane >> 5; const int wid = __builtin_amdgcn_readfirstlane(tid >> 6);
;   LAS char* Kl = lds + LDS_K; LAS char* Vl = lds + LDS_V;
;   LAS float* ws = (LAS float*)(lds + LDS_WS) + wid * 64; LAS float* li_l = ws; LAS float* al_l = ws + 32;
;   const bf16_t* Kw = KV + (rowbase + lane) * LDKV + h * 128 + wid * 8;
;   const bf16_t* KRw = KR + (rowbase + lane) * LDKR + (wid & 3) * 8;
;   const bf16_t* Vw = KV + (rowbase + 16 * (wid & 3) + (lane >> 2)) * LDKV + h * 128 + 64 + (wid >> 2) * 32 + (lane & 3) * 8;
;     ...
;   float m_reg = -1e30f, l_reg = 0; f32x16 o[2] = {}; bf16x8 qr[6];
;   const bf16_t* Qw = Q + (rowbase + q0 + wid * QBLK + r32) * LDQ + h * QKD + hi * 8;
; #pragma unroll
;   for (int d0 = 0; d0 < 6; ++d0) qr[d0] = *reinterpret_cast<const bf16x8*>(Qw + d0 * 16);
;   asm volatile("" ::: "memory");
;   ISSUE(0, 0, 0); ISSUE(1, KSLOT, VSLOT);
;   const int vbase = (int)(unsigned)(uintptr_t)Vl + ((lane >> 4) & 1) * 32 + (lane & 3) * 8 + (4 * hi + ((lane & 15) >> 2)) * 64;
;   f32x16 pA0, pA1, pB0, pB1; float mnA, mnB, alA, alB; bf16x8 pa0, pa1, pa2, pa3; constexpr int NT = SEQ / KVBLK;
;   int kprev = 2 * KSLOT, kcur = 0, knext = KSLOT;
;     ...
;   bf16x8 kf[12]; s16x4 vf[16];
;   VMW_PART(); BAR();
;   if (wid >= 4) BAR();
;   ISSUE(2, 2 * KSLOT, 2 * VSLOT); kload12(kf, Kl, r32, hi); VMW_PART(); BAR();
	s_cbranch_scc0 .LBB0_605
.LBB0_553:
	s_ashr_i32 s58, s22, 7
	v_readfirstlane_b32 s68, v195
	s_ashr_i32 s59, s58, 31
	s_lshl_b32 s6, s22, 8
	s_lshr_b32 s35, s68, 6
	s_bfe_u32 s34, s22, 0x30004
	s_lshl_b64 s[4:5], s[58:59], 12
	s_and_b32 s52, s6, 0xf00
	s_lshl_b32 s56, s35, 4
	s_and_b32 s60, s56, 48
	s_lshl_b32 s6, s34, 8
	s_or_b32 s52, s4, s52
	s_lshl_b32 s53, s35, 5
	s_add_u32 s52, s52, s53
	v_or_b32_e32 v2, s52, v192
	s_movk_i32 s57, 0x600
	s_addc_u32 s53, s5, 0
	v_mad_u64_u32 v[2:3], s[62:63], v2, s57, v[218:219]
	v_mad_i32_i24 v3, s53, v240, v3
	s_mul_i32 s62, s34, 0xc0
	s_mov_b32 s63, s7
	v_lshl_add_u64 v[2:3], v[2:3], 0, s[62:63]
	v_lshl_add_u64 v[2:3], v[2:3], 0, v[206:207]
	v_mov_b32_e32 v5, s5
	v_or_b32_e32 v4, s4, v194
	global_load_dwordx4 v[116:119], v[2:3], off
	global_load_dwordx4 v[112:115], v[2:3], off offset:32
	global_load_dwordx4 v[108:111], v[2:3], off offset:64
	global_load_dwordx4 v[104:107], v[2:3], off offset:96
	global_load_dwordx4 v[100:103], v[2:3], off offset:128
	global_load_dwordx4 v[96:99], v[2:3], off offset:160
	v_lshlrev_b64 v[0:1], 11, v[4:5]
	v_lshl_add_u64 v[0:1], s[42:43], 0, v[0:1]
	s_lshl_b32 s64, s35, 10
	v_lshl_add_u64 v[0:1], v[0:1], 0, s[6:7]
	s_mov_b32 s57, s7
	s_add_i32 s65, s64, 0
	v_lshl_add_u64 v[0:1], v[0:1], 0, s[56:57]
	v_or_b32_e32 v2, s60, v193
	v_or_b32_e32 v2, s4, v2
	v_mov_b32_e32 v3, s5
	v_lshlrev_b64 v[2:3], 11, v[2:3]
	v_lshl_add_u64 v[2:3], s[42:43], 0, v[2:3]
	s_lshr_b32 s84, s68, 2
	v_lshl_add_u64 v[2:3], v[2:3], 0, s[6:7]
	s_and_b32 s6, s84, 0x3fffffc0
	s_cmpk_lt_u32 s68, 0x100
	v_lshl_add_u64 v[2:3], v[2:3], 0, s[6:7]
	s_cselect_b64 s[62:63], -1, 0
	s_cmpk_gt_u32 s68, 0xff
	v_lshl_add_u64 v[2:3], v[2:3], 0, v[208:209]
	s_cselect_b64 s[56:57], -1, 0
	s_mov_b64 s[4:5], 0x80
	v_lshl_add_u64 v[2:3], v[2:3], 0, s[4:5]
	v_lshlrev_b64 v[4:5], 6, v[4:5]
	v_lshl_add_u64 v[4:5], s[46:47], 0, v[4:5]
	s_mov_b32 s61, s7
	v_lshl_add_u64 v[4:5], v[4:5], 0, s[60:61]
	s_mov_b64 s[4:5], s[56:57]
	s_and_b64 vcc, exec, s[4:5]
	s_cbranch_vccnz .Lpr_nr0
	s_add_i32 m0, s65, 0x2000
	s_nop 0
	global_load_lds_dwordx4 v[4:5], off
	s_mov_b64 s[98:99], 0x1000
	v_lshl_add_u64 v[6:7], v[4:5], 0, s[98:99]
	s_add_i32 m0, s65, 0x5000
	s_nop 0
	global_load_lds_dwordx4 v[6:7], off
	v_lshl_add_u64 v[6:7], v[4:5], 0, s[12:13]
	s_add_i32 m0, s65, 0x8000
	s_nop 0
	global_load_lds_dwordx4 v[6:7], off
.Lpr_nr0:
	s_mov_b32 m0, s65
	s_nop 0
	global_load_lds_dwordx4 v[0:1], off
	s_add_i32 m0, s65, 0xc000
	s_nop 0
	global_load_lds_dwordx4 v[2:3], off
	v_lshl_add_u64 v[6:7], v[0:1], 0, s[8:9]
	s_add_i32 m0, s65, 0x3000
	s_nop 0
	global_load_lds_dwordx4 v[6:7], off
	v_lshl_add_u64 v[6:7], v[2:3], 0, s[8:9]
	s_add_i32 m0, s65, 0xe000
	s_nop 0
	global_load_lds_dwordx4 v[6:7], off
	v_lshl_add_u64 v[6:7], v[0:1], 0, s[10:11]
	s_add_i32 m0, s65, 0x6000
	s_nop 0
	global_load_lds_dwordx4 v[6:7], off
	v_lshl_add_u64 v[6:7], v[2:3], 0, s[10:11]
	s_add_i32 m0, s65, 0x10000
	s_nop 0
	global_load_lds_dwordx4 v[6:7], off
	s_waitcnt vmcnt(4) lgkmcnt(0)
	s_barrier
	s_cmpk_lt_u32 s68, 0x100
	s_cbranch_scc1 .Lpr_nostag
	s_barrier
.Lpr_nostag:
	s_and_b64 vcc, exec, s[4:5]
	s_cbranch_vccnz .Lpr_nr3
	s_mov_b64 s[98:99], 0x3000
	v_lshl_add_u64 v[6:7], v[4:5], 0, s[98:99]
	s_add_i32 m0, s65, 0xb000
	s_nop 0
	global_load_lds_dwordx4 v[6:7], off
.Lpr_nr3:
	s_mov_b64 s[98:99], 0x60000
	v_lshl_add_u64 v[6:7], v[0:1], 0, s[98:99]
	s_add_i32 m0, s65, 0x9000
	s_nop 0
	global_load_lds_dwordx4 v[6:7], off
	v_lshl_add_u64 v[6:7], v[2:3], 0, s[98:99]
	s_add_i32 m0, s65, 0x12000
	s_nop 0
	global_load_lds_dwordx4 v[6:7], off
	ds_read_b128 v[16:19], v231
	ds_read_b128 v[20:23], v231 offset:512
	ds_read_b128 v[68:71], v231 offset:2048
	ds_read_b128 v[64:67], v231 offset:2560
	ds_read_b128 v[60:63], v231 offset:4096
	ds_read_b128 v[56:59], v231 offset:4608
	ds_read_b128 v[12:15], v231 offset:6144
	ds_read_b128 v[8:11], v231 offset:6656
	ds_read_b128 v[4:7], v231 offset:8192
	ds_read_b128 v[52:55], v231 offset:8704
	ds_read_b128 v[0:3], v231 offset:10240
	ds_read_b128 v[48:51], v231 offset:10752
	s_and_b64 vcc, exec, s[56:57]
	s_cbranch_vccnz .Lpr_wh
	s_waitcnt vmcnt(5) lgkmcnt(0)
	s_branch .Lpr_wd
.Lpr_wh:
	s_waitcnt vmcnt(4) lgkmcnt(0)
.Lpr_wd:
	s_and_b32 s62, s68, 0x3fffffc0
	s_lshl_b32 s62, s62, 2
	s_lshr_b32 s61, s22, 4
	s_and_b32 s61, s61, 7
	s_add_i32 s62, s62, 0x18000
	s_lshl_b32 s61, s61, 8
	s_barrier
; #define FMA_S(x) asm("v_fma_f32 %0, %1, %2, %3" : "=v"(x) : "v"(x), "v"(Cv), "v"(mnC))
; #define KROT() do { const int t_ = kprev; kprev = kcur; kcur = knext; knext = t_; } while (0)
; #define BAR() do { SBAR(); __builtin_amdgcn_s_barrier(); asm volatile("" ::: "memory"); SBAR(); } while (0)
; __device__ __forceinline__ void partialSM(f32x16& p0, f32x16& p1, float& m_reg, float& mn, float& alpha) {
;   constexpr float C = SCALE * 1.4426950408889634f;
;   float pmax = p0[0];
; #pragma unroll
;   for (int r = 1; r < 16; ++r) pmax = fmaxf(pmax, p0[r]);
; #pragma unroll
;   for (int r = 0; r < 16; ++r) pmax = fmaxf(pmax, p1[r]);
;   { auto rr = __builtin_amdgcn_permlane32_swap(__float_as_uint(pmax), __float_as_uint(pmax), false, false);
;     pmax = fmaxf(__uint_as_float(rr[0]), __uint_as_float(rr[1])); }
;   if (__builtin_expect(__all(pmax - m_reg <= THR / SCALE), 1)) { mn = m_reg; alpha = 1.f; }
;   else { mn = fmaxf(m_reg, pmax); alpha = __builtin_amdgcn_exp2f((m_reg - mn) * C); m_reg = mn; }
;   const float mnC = -mn * C;
;     ...
;   float Cv = C; asm volatile("" : "+v"(Cv));
; #pragma unroll
;   for (int r = 0; r < 16; ++r) FMA_S(p0[r]);
; #pragma unroll
;   for (int r = 0; r < 16; ++r) FMA_S(p1[r]);
;     ...
; #pragma unroll
;   for (int r = 0; r < 16; ++r) p0[r] = __builtin_amdgcn_exp2f(p0[r]);
; template <int MODE> __device__ __forceinline__ void attn_unit(const bf16_t* __restrict__ Q, const bf16_t* __restrict__ KV, const bf16_t* __restrict__ KR, bf16_t* __restrict__ O,
;                                           long rowbase, int q0, int h, LAS char* lds) {
;     ...
;   qkt3(pA0, pA1, kf, qr); partialSM(pA0, pA1, m_reg, mnA, alA); asm volatile("" : "+v"(pA0), "+v"(pA1)); KROT(); BAR();
	s_waitcnt lgkmcnt(0)
	v_mfma_f32_32x32x16_bf16 v[80:95], v[16:19], v[116:119], 0
	s_mov_b32 s68, 0
	s_mov_b32 s69, s68
	v_mfma_f32_32x32x16_bf16 v[80:95], v[68:71], v[112:115], v[80:95]
	s_mov_b32 s70, s68
	s_mov_b32 s71, s68
	v_mfma_f32_32x32x16_bf16 v[32:47], v[20:23], v[116:119], 0
	s_mov_b32 s72, s68
	s_mov_b32 s73, s68
	v_mfma_f32_32x32x16_bf16 v[80:95], v[60:63], v[108:111], v[80:95]
	s_mov_b32 s74, s68
	s_mov_b32 s75, s68
	v_mfma_f32_32x32x16_bf16 v[32:47], v[64:67], v[112:115], v[32:47]
	s_mov_b32 s76, s68
	s_mov_b32 s77, s68
	v_mfma_f32_32x32x16_bf16 v[80:95], v[12:15], v[104:107], v[80:95]
	s_mov_b32 s78, s68
	s_mov_b32 s79, s68
	v_mfma_f32_32x32x16_bf16 v[32:47], v[56:59], v[108:111], v[32:47]
	s_mov_b32 s80, s68
	s_mov_b32 s81, s68
	v_mfma_f32_32x32x16_bf16 v[80:95], v[4:7], v[100:103], v[80:95]
	s_mov_b32 s82, s68
	s_mov_b32 s83, s68
	v_mfma_f32_32x32x16_bf16 v[32:47], v[8:11], v[104:107], v[32:47]
	v_mfma_f32_32x32x16_bf16 v[80:95], v[0:3], v[96:99], v[80:95]
	v_mfma_f32_32x32x16_bf16 v[32:47], v[52:55], v[100:103], v[32:47]
	v_mfma_f32_32x32x16_bf16 v[32:47], v[48:51], v[96:99], v[32:47]
	v_mov_b32_e32 v246, 0
	v_mov_b32_e32 v247, 0
	v_mov_b32_e32 v248, 0
	v_mov_b32_e32 v250, 0
	v_mov_b32_e32 v245, 0x3f80
	v_cndmask_b32_e64 v249, 0, v245, s[2:3]
	v_mov_b64_e32 v[0:1], 0
	v_mov_b64_e32 v[2:3], 0
	v_mov_b64_e32 v[4:5], 0
	v_mov_b64_e32 v[6:7], 0
	v_mov_b64_e32 v[8:9], 0
	v_mov_b64_e32 v[10:11], 0
	v_mov_b64_e32 v[12:13], 0
	v_mov_b64_e32 v[14:15], 0
	v_max3_f32 v252, v80, v81, v82
	v_max3_f32 v252, v252, v83, v84
	v_max3_f32 v252, v252, v85, v86
	v_max3_f32 v252, v252, v87, v88
	v_max3_f32 v252, v252, v89, v90
	v_max3_f32 v252, v252, v91, v92
	v_max3_f32 v252, v252, v93, v94
	v_max3_f32 v252, v252, v95, v32
	v_max3_f32 v252, v252, v33, v34
	v_max3_f32 v252, v252, v35, v36
	v_max3_f32 v252, v252, v37, v38
	v_max3_f32 v252, v252, v39, v40
	v_max3_f32 v252, v252, v41, v42
	v_max3_f32 v252, v252, v43, v44
	v_max3_f32 v252, v252, v45, v46
	v_max_f32_e32 v252, v252, v47
	v_mov_b32_e32 v253, v252
	s_nop 1
	v_permlane32_swap_b32_e32 v252, v253
	v_max_f32_e32 v252, v252, v253
	v_and_b32_e32 v253, 0xffff0000, v252
	v_xor_b32_e32 v255, 0x80000000, v253
	v_lshrrev_b32_e32 v251, 16, v255
	v_sub_f32_e32 v64, v32, v253
	v_sub_f32_e32 v65, v33, v253
	v_sub_f32_e32 v66, v34, v253
	v_sub_f32_e32 v67, v35, v253
	v_sub_f32_e32 v68, v36, v253
	v_sub_f32_e32 v69, v37, v253
	v_sub_f32_e32 v70, v38, v253
	v_sub_f32_e32 v71, v39, v253
	v_sub_f32_e32 v72, v40, v253
	v_sub_f32_e32 v73, v41, v253
	v_sub_f32_e32 v74, v42, v253
	v_sub_f32_e32 v75, v43, v253
	v_sub_f32_e32 v76, v44, v253
	v_sub_f32_e32 v77, v45, v253
	v_sub_f32_e32 v78, v46, v253
	v_sub_f32_e32 v79, v47, v253
	v_sub_f32_e32 v152, v80, v253
	v_sub_f32_e32 v153, v81, v253
	v_exp_f32_e32 v32, v152
	v_sub_f32_e32 v152, v82, v253
	v_exp_f32_e32 v33, v153
	v_sub_f32_e32 v153, v83, v253
	v_exp_f32_e32 v34, v152
	v_sub_f32_e32 v152, v84, v253
	v_exp_f32_e32 v35, v153
	v_sub_f32_e32 v153, v85, v253
	v_exp_f32_e32 v36, v152
	v_sub_f32_e32 v152, v86, v253
	v_exp_f32_e32 v37, v153
	v_sub_f32_e32 v153, v87, v253
	v_exp_f32_e32 v38, v152
	v_sub_f32_e32 v152, v88, v253
	v_exp_f32_e32 v39, v153
	v_sub_f32_e32 v153, v89, v253
	v_exp_f32_e32 v40, v152
	v_sub_f32_e32 v152, v90, v253
	v_exp_f32_e32 v41, v153
	v_sub_f32_e32 v153, v91, v253
	v_exp_f32_e32 v42, v152
	v_sub_f32_e32 v152, v92, v253
	v_exp_f32_e32 v43, v153
	v_sub_f32_e32 v153, v93, v253
	v_exp_f32_e32 v44, v152
	v_sub_f32_e32 v152, v94, v253
	v_exp_f32_e32 v45, v153
	v_sub_f32_e32 v153, v95, v253
	v_exp_f32_e32 v46, v152
	v_exp_f32_e32 v47, v153
	s_nop 0
	s_barrier
	s_lshl_b64 s[70:71], s[58:59], 18
	s_and_b32 s63, s84, 48
	s_or_b32 s70, s70, s63
	s_lshl_b64 s[58:59], s[58:59], 23
	v_lshl_add_u64 v[220:221], s[70:71], 0, v[200:201]
	s_add_u32 s70, s6, s61
	s_addc_u32 s71, 0, 0
	s_and_b32 s6, s84, 0x3ffffff0
	s_add_u32 s6, s6, s61
	v_or_b32_e32 v16, s58, v202
	v_add_u32_e32 v18, s60, v193
	s_addc_u32 s60, 0, 0
	v_mov_b32_e32 v17, s59
	v_lshl_or_b32 v16, v18, 11, v16
	s_add_u32 s58, s6, s58
	v_lshl_add_u64 v[222:223], s[70:71], 0, v[16:17]
	s_addc_u32 s59, s60, s59
	v_mov_b64_e32 v[30:31], v[14:15]
	v_lshl_add_u32 v211, v192, 2, s62
	v_lshl_add_u64 v[224:225], s[58:59], 0, v[204:205]
	v_mov_b32_e32 v213, 0
	s_mov_b32 s6, 1
	s_movk_i32 s70, 0x6000
	s_movk_i32 s69, 0x3000
	s_mov_b32 s63, 0x8000
	v_mov_b64_e32 v[28:29], v[12:13]
	v_mov_b64_e32 v[26:27], v[10:11]
	v_mov_b64_e32 v[24:25], v[8:9]
	v_mov_b64_e32 v[22:23], v[6:7]
	v_mov_b64_e32 v[20:21], v[4:5]
	v_mov_b64_e32 v[18:19], v[2:3]
	v_mov_b64_e32 v[16:17], v[0:1]
	s_mov_b32 s98, 0
	s_mov_b32 s99, 0x3000
	s_mov_b32 s100, 0x8000
	s_mov_b32 s101, 0
.LBB0_570:
	v_lshl_add_u64 v[226:227], s[28:29], 0, v[224:225]
	v_lshl_add_u64 v[228:229], s[28:29], 0, v[222:223]
	s_cmp_gt_u32 s6, 60
	s_cbranch_scc1 .Lni_a
	s_mov_b64 s[60:61], 0x1fc84000
	v_lshl_add_u64 v[56:57], v[226:227], 0, s[60:61]
	s_add_i32 m0, s65, s98
	s_nop 0
	global_load_lds_dwordx4 v[56:57], off
	s_and_b64 vcc, exec, s[4:5]
	s_cbranch_vccnz .Lnr_a
	v_lshl_add_u64 v[56:57], s[28:29], 0, v[220:221]
	v_lshl_add_u64 v[56:57], v[56:57], 0, s[14:15]
	s_add_i32 s60, s65, s98
	s_add_i32 m0, s60, 0x2000
	s_nop 0
	global_load_lds_dwordx4 v[56:57], off
.Lnr_a:
	v_lshl_add_u64 v[56:57], v[228:229], 0, s[16:17]
	s_add_i32 s60, s65, s100
	s_add_i32 m0, s60, 0xc000
	s_nop 0
	global_load_lds_dwordx4 v[56:57], off
; __device__ __forceinline__ void finishSM2(f32x16& p0, f32x16& p1, float alpha, float& l_reg, bf16x8& pa0, bf16x8& pa1, bf16x8& pa2, bf16x8& pa3) {
; #pragma unroll
;   for (int r = 0; r < 16; ++r) p1[r] = __builtin_amdgcn_exp2f(p1[r]);
;   float ps = 0;
; #pragma unroll
;   for (int r = 0; r < 16; ++r) ps += p0[r];
; #pragma unroll
;   for (int r = 0; r < 16; ++r) ps += p1[r];
;   { auto rr = __builtin_amdgcn_permlane32_swap(__float_as_uint(ps), __float_as_uint(ps), false, false);
;     ps = __uint_as_float(rr[0]) + __uint_as_float(rr[1]); }
;   l_reg = l_reg * alpha + ps;
;     ...
;   PK8(p0, 0, pa0); PK8(p0, 8, pa1); PK8(p1, 0, pa2); PK8(p1, 8, pa3);
;     ...
; }
; __device__ __forceinline__ void kload12(bf16x8* kf, const LAS char* Ks, int r32, int hi) {
;   const LAS char* kb = Ks + hi * 1024 + r32 * 16;
; #pragma unroll
;   for (int d0 = 0; d0 < 6; ++d0) { kf[2 * d0] = *(const LAS bf16x8*)(kb + d0 * 2048); kf[2 * d0 + 1] = *(const LAS bf16x8*)(kb + d0 * 2048 + 512); }
; }
; __device__ __forceinline__ void qkt3(f32x16& p0, f32x16& p1, const bf16x8* kf, const bf16x8* qr) {
;   p0 = f32x16{}; p1 = f32x16{};
; #pragma unroll
;   for (int d0 = 0; d0 < 6; ++d0) {
;     p0 = __builtin_amdgcn_mfma_f32_32x32x16_bf16(kf[2 * d0], qr[d0], p0, 0, 0, 0);
;     p1 = __builtin_amdgcn_mfma_f32_32x32x16_bf16(kf[2 * d0 + 1], qr[d0], p1, 0, 0, 0); }
; }
; __device__ __forceinline__ void vload16(s16x4* vf, int vb) {
;   vf[0] = tr_read<0>(vb); vf[1] = tr_read<512>(vb); vf[2] = tr_read<1024>(vb); vf[3] = tr_read<1536>(vb);
;   vf[4] = tr_read<2048>(vb); vf[5] = tr_read<2560>(vb); vf[6] = tr_read<3072>(vb); vf[7] = tr_read<3584>(vb);
;   vf[8] = tr_read<4096>(vb); vf[9] = tr_read<4608>(vb); vf[10] = tr_read<5120>(vb); vf[11] = tr_read<5632>(vb);
;   vf[12] = tr_read<6144>(vb); vf[13] = tr_read<6656>(vb); vf[14] = tr_read<7168>(vb); vf[15] = tr_read<7680>(vb);
; }
; __device__ __forceinline__ void pv3(f32x16* o, const s16x4* vf, bf16x8 pa0, bf16x8 pa1, bf16x8 pa2, bf16x8 pa3) {
;     ...
;   o[0] = __builtin_amdgcn_mfma_f32_32x32x16_bf16(pa0, PKV(0), o[0], 0, 0, 0);
;   o[1] = __builtin_amdgcn_mfma_f32_32x32x16_bf16(pa0, PKV(8), o[1], 0, 0, 0);
;   o[0] = __builtin_amdgcn_mfma_f32_32x32x16_bf16(pa1, PKV(2), o[0], 0, 0, 0);
;   o[1] = __builtin_amdgcn_mfma_f32_32x32x16_bf16(pa1, PKV(10), o[1], 0, 0, 0);
;   o[0] = __builtin_amdgcn_mfma_f32_32x32x16_bf16(pa2, PKV(4), o[0], 0, 0, 0);
.Lni_a:
	v_add_u32_e32 v217, s101, v197
	v_add3_u32 v58, s99, v203, v230
	ds_read_b128 v[48:51], v58
	ds_read_b128 v[52:55], v58 offset:512
	ds_read_b128 v[188:191], v58 offset:2048
	ds_read_b128 v[184:187], v58 offset:2560
	ds_read_b128 v[180:183], v58 offset:4096
	ds_read_b128 v[176:179], v58 offset:4608
	ds_read_b128 v[172:175], v58 offset:6144
	ds_read_b128 v[168:171], v58 offset:6656
	ds_read_b128 v[164:167], v58 offset:8192
	ds_read_b128 v[160:163], v58 offset:8704
	ds_read_b128 v[156:159], v58 offset:10240
	ds_read_b128 v[152:155], v58 offset:10752
	s_add_i32 s98, s98, 0x3000
	s_cmp_eq_u32 s98, 0xc000
	s_cselect_b32 s98, 0, s98
	s_add_i32 s99, s99, 0x3000
	s_cmp_eq_u32 s99, 0xc000
	s_cselect_b32 s99, 0, s99
	s_add_i32 s100, s100, 0x2000
	s_cmp_eq_u32 s100, 0xc000
	s_cselect_b32 s100, 0, s100
	s_add_i32 s101, s101, 0x2000
	s_cmp_eq_u32 s101, 0xc000
	s_cselect_b32 s101, 0, s101
	s_cmp_gt_u32 s6, 60
	s_cbranch_scc1 .Lwl_a
	s_and_b64 vcc, exec, s[56:57]
	s_cbranch_vccnz .Lwh_a
	s_waitcnt vmcnt(6) lgkmcnt(0)
	s_branch .Lwd_a
.Lwh_a:
	s_waitcnt vmcnt(4) lgkmcnt(0)
	s_branch .Lwd_a
.Lwl_a:
	s_and_b64 vcc, exec, s[56:57]
	s_cbranch_vccnz .Lwlh_a
	s_waitcnt vmcnt(3) lgkmcnt(0)
	s_branch .Lwd_a
.Lwlh_a:
	s_waitcnt vmcnt(2) lgkmcnt(0)
.Lwd_a:
	s_barrier
	s_waitcnt lgkmcnt(0)
	v_mfma_f32_32x32x16_bf16 v[80:95], v[246:249], v[248:251], 0
	v_exp_f32_e32 v64, v64
	v_add_f32_e32 v213, v32, v213
	ds_read_b64_tr_b16 v[148:149], v217 offset:0
	v_exp_f32_e32 v65, v65
	v_add_f32_e32 v213, v33, v213
	ds_read_b64_tr_b16 v[150:151], v217 offset:512
	v_mfma_f32_32x32x16_bf16 v[80:95], v[48:51], v[116:119], v[80:95]
	v_exp_f32_e32 v66, v66
	v_add_f32_e32 v213, v34, v213
	ds_read_b64_tr_b16 v[140:141], v217 offset:1024
	v_exp_f32_e32 v67, v67
	v_add_f32_e32 v213, v35, v213
	ds_read_b64_tr_b16 v[142:143], v217 offset:1536
	v_mfma_f32_32x32x16_bf16 v[48:63], v[52:55], v[116:119], 0
	v_exp_f32_e32 v68, v68
	v_add_f32_e32 v213, v36, v213
	ds_read_b64_tr_b16 v[132:133], v217 offset:2048
	v_exp_f32_e32 v69, v69
	v_add_f32_e32 v213, v37, v213
	ds_read_b64_tr_b16 v[134:135], v217 offset:2560
	v_mfma_f32_32x32x16_bf16 v[48:63], v[246:249], v[248:251], v[48:63]
	v_exp_f32_e32 v70, v70
	v_add_f32_e32 v213, v38, v213
	ds_read_b64_tr_b16 v[124:125], v217 offset:3072
	v_exp_f32_e32 v71, v71
	v_add_f32_e32 v213, v39, v213
	ds_read_b64_tr_b16 v[126:127], v217 offset:3584
	v_mfma_f32_32x32x16_bf16 v[80:95], v[188:191], v[112:115], v[80:95]
	v_exp_f32_e32 v72, v72
	v_add_f32_e32 v213, v40, v213
	ds_read_b64_tr_b16 v[144:145], v217 offset:4096
	v_exp_f32_e32 v73, v73
	v_add_f32_e32 v213, v41, v213
	ds_read_b64_tr_b16 v[146:147], v217 offset:4608
	v_mfma_f32_32x32x16_bf16 v[48:63], v[184:187], v[112:115], v[48:63]
	v_exp_f32_e32 v74, v74
	v_add_f32_e32 v213, v42, v213
	ds_read_b64_tr_b16 v[136:137], v217 offset:5120
	v_exp_f32_e32 v75, v75
	v_add_f32_e32 v213, v43, v213
	ds_read_b64_tr_b16 v[138:139], v217 offset:5632
	v_mfma_f32_32x32x16_bf16 v[80:95], v[180:183], v[108:111], v[80:95]
	v_exp_f32_e32 v76, v76
	v_add_f32_e32 v213, v44, v213
	ds_read_b64_tr_b16 v[128:129], v217 offset:6144
	v_exp_f32_e32 v77, v77
	v_add_f32_e32 v213, v45, v213
	ds_read_b64_tr_b16 v[130:131], v217 offset:6656
	v_mfma_f32_32x32x16_bf16 v[48:63], v[176:179], v[108:111], v[48:63]
	v_exp_f32_e32 v78, v78
	v_add_f32_e32 v213, v46, v213
	ds_read_b64_tr_b16 v[120:121], v217 offset:7168
	v_exp_f32_e32 v79, v79
	v_add_f32_e32 v213, v47, v213
	ds_read_b64_tr_b16 v[122:123], v217 offset:7680
	v_mfma_f32_32x32x16_bf16 v[80:95], v[172:175], v[104:107], v[80:95]
	v_add_f32_e32 v245, v64, v65
	v_add_f32_e32 v245, v66, v245
	v_add_f32_e32 v245, v67, v245
	v_add_f32_e32 v245, v68, v245
	v_add_f32_e32 v245, v69, v245
	v_add_f32_e32 v245, v70, v245
	v_mfma_f32_32x32x16_bf16 v[48:63], v[168:171], v[104:107], v[48:63]
	v_add_f32_e32 v245, v71, v245
	v_add_f32_e32 v245, v72, v245
	v_add_f32_e32 v245, v73, v245
	v_add_f32_e32 v245, v74, v245
	v_add_f32_e32 v245, v75, v245
	v_mfma_f32_32x32x16_bf16 v[80:95], v[164:167], v[100:103], v[80:95]
	v_add_f32_e32 v245, v76, v245
	v_add_f32_e32 v245, v77, v245
	v_add_f32_e32 v245, v78, v245
	v_add_f32_e32 v245, v79, v245
	v_add_f32_e32 v213, v245, v213
	v_mfma_f32_32x32x16_bf16 v[48:63], v[160:163], v[100:103], v[48:63]
	v_cvt_pk_bf16_f32 v32, v32, v33
	v_cvt_pk_bf16_f32 v33, v34, v35
	v_cvt_pk_bf16_f32 v34, v36, v37
	v_cvt_pk_bf16_f32 v35, v38, v39
	v_cvt_pk_bf16_f32 v36, v40, v41
	v_cvt_pk_bf16_f32 v37, v42, v43
	v_mfma_f32_32x32x16_bf16 v[80:95], v[156:159], v[96:99], v[80:95]
	v_cvt_pk_bf16_f32 v38, v44, v45
	v_cvt_pk_bf16_f32 v39, v46, v47
	v_cvt_pk_bf16_f32 v64, v64, v65
	v_cvt_pk_bf16_f32 v65, v66, v67
	v_cvt_pk_bf16_f32 v66, v68, v69
	v_cvt_pk_bf16_f32 v67, v70, v71
	v_mfma_f32_32x32x16_bf16 v[48:63], v[152:155], v[96:99], v[48:63]
	v_cvt_pk_bf16_f32 v68, v72, v73
	v_cvt_pk_bf16_f32 v69, v74, v75
	v_cvt_pk_bf16_f32 v70, v76, v77
	v_cvt_pk_bf16_f32 v71, v78, v79
	s_waitcnt lgkmcnt(0)
	v_mfma_f32_32x32x16_bf16 v[0:15], v[32:35], v[148:151], v[0:15]
	v_exp_f32_e32 v40, v88
	v_exp_f32_e32 v41, v89
	v_max3_f32 v252, v80, v81, v82
	v_mfma_f32_32x32x16_bf16 v[16:31], v[32:35], v[144:147], v[16:31]
	v_exp_f32_e32 v42, v90
	v_exp_f32_e32 v43, v91
	v_max3_f32 v252, v252, v83, v84
	v_max3_f32 v252, v252, v85, v86
	v_mfma_f32_32x32x16_bf16 v[0:15], v[36:39], v[140:143], v[0:15]
	v_exp_f32_e32 v44, v92
	v_exp_f32_e32 v45, v93
	v_max3_f32 v252, v252, v87, v88
	v_max3_f32 v252, v252, v89, v90
	v_mfma_f32_32x32x16_bf16 v[16:31], v[36:39], v[136:139], v[16:31]
	v_exp_f32_e32 v46, v94
	v_exp_f32_e32 v47, v95
	v_max3_f32 v252, v252, v91, v92
	v_max3_f32 v252, v252, v93, v94
	v_mfma_f32_32x32x16_bf16 v[0:15], v[64:67], v[132:135], v[0:15]
	v_exp_f32_e32 v32, v80
	v_exp_f32_e32 v33, v81
	v_max3_f32 v252, v252, v95, v48
	v_max3_f32 v252, v252, v49, v50
	v_mfma_f32_32x32x16_bf16 v[16:31], v[64:67], v[128:131], v[16:31]
	v_exp_f32_e32 v34, v82
	v_exp_f32_e32 v35, v83
	v_max3_f32 v252, v252, v51, v52
	v_max3_f32 v252, v252, v53, v54
	v_mfma_f32_32x32x16_bf16 v[0:15], v[68:71], v[124:127], v[0:15]
	v_exp_f32_e32 v36, v84
	v_exp_f32_e32 v37, v85
	v_max3_f32 v252, v252, v55, v56
	v_max3_f32 v252, v252, v57, v58
	v_mfma_f32_32x32x16_bf16 v[16:31], v[68:71], v[120:123], v[16:31]
	v_max3_f32 v252, v252, v59, v60
	v_max3_f32 v252, v252, v61, v62
	v_max_f32_e32 v252, v252, v63
	v_cmp_nge_f32_e32 vcc, s23, v252
	v_exp_f32_e32 v38, v86
	v_exp_f32_e32 v39, v87
	s_nop 0
	s_cmp_lg_u64 vcc, 0
	s_cbranch_scc1 .Lrare_a
; #define LAS __attribute__((address_space(3)))
; __device__ __forceinline__ void kload12(bf16x8* kf, const LAS char* Ks, int r32, int hi) {
;   const LAS char* kb = Ks + hi * 1024 + r32 * 16;
; #pragma unroll
;   for (int d0 = 0; d0 < 6; ++d0) { kf[2 * d0] = *(const LAS bf16x8*)(kb + d0 * 2048); kf[2 * d0 + 1] = *(const LAS bf16x8*)(kb + d0 * 2048 + 512); }
; }
; __device__ __forceinline__ void qkt3(f32x16& p0, f32x16& p1, const bf16x8* kf, const bf16x8* qr) {
;   p0 = f32x16{}; p1 = f32x16{};
; #pragma unroll
;   for (int d0 = 0; d0 < 6; ++d0) {
;     p0 = __builtin_amdgcn_mfma_f32_32x32x16_bf16(kf[2 * d0], qr[d0], p0, 0, 0, 0);
;     p1 = __builtin_amdgcn_mfma_f32_32x32x16_bf16(kf[2 * d0 + 1], qr[d0], p1, 0, 0, 0); }
; }
; __device__ __forceinline__ void vload16(s16x4* vf, int vb) {
;   vf[0] = tr_read<0>(vb); vf[1] = tr_read<512>(vb); vf[2] = tr_read<1024>(vb); vf[3] = tr_read<1536>(vb);
;   vf[4] = tr_read<2048>(vb); vf[5] = tr_read<2560>(vb); vf[6] = tr_read<3072>(vb); vf[7] = tr_read<3584>(vb);
;   vf[8] = tr_read<4096>(vb); vf[9] = tr_read<4608>(vb); vf[10] = tr_read<5120>(vb); vf[11] = tr_read<5632>(vb);
;   vf[12] = tr_read<6144>(vb); vf[13] = tr_read<6656>(vb); vf[14] = tr_read<7168>(vb); vf[15] = tr_read<7680>(vb);
; }
.Ljoin_a:
	s_barrier
	s_cmp_gt_u32 s6, 60
	s_cselect_b64 s[58:59], -1, 0
	s_cmp_gt_u32 s6, 60
	s_cbranch_scc1 .Lni_b
	v_lshl_add_u64 v[64:65], v[226:227], 0, s[18:19]
	s_add_i32 m0, s65, s98
	s_nop 0
	global_load_lds_dwordx4 v[64:65], off
	s_and_b64 vcc, exec, s[4:5]
	s_cbranch_vccnz .Lnr_b
	v_lshl_add_u64 v[64:65], s[28:29], 0, v[220:221]
	v_lshl_add_u64 v[64:65], v[64:65], 0, s[24:25]
	s_add_i32 s60, s65, s98
	s_add_i32 m0, s60, 0x2000
	s_nop 0
	global_load_lds_dwordx4 v[64:65], off
.Lnr_b:
	v_lshl_add_u64 v[64:65], v[228:229], 0, s[54:55]
	s_add_i32 s60, s65, s100
	s_add_i32 m0, s60, 0xc000
	s_nop 0
	global_load_lds_dwordx4 v[64:65], off
.Lni_b:
	v_add_u32_e32 v217, s101, v197
	v_add3_u32 v72, s99, v203, v230
	ds_read_b128 v[64:67], v72
	ds_read_b128 v[68:71], v72 offset:512
	ds_read_b128 v[188:191], v72 offset:2048
	ds_read_b128 v[184:187], v72 offset:2560
	ds_read_b128 v[180:183], v72 offset:4096
	ds_read_b128 v[176:179], v72 offset:4608
	ds_read_b128 v[172:175], v72 offset:6144
	ds_read_b128 v[168:171], v72 offset:6656
	ds_read_b128 v[164:167], v72 offset:8192
	ds_read_b128 v[160:163], v72 offset:8704
	ds_read_b128 v[156:159], v72 offset:10240
	ds_read_b128 v[152:155], v72 offset:10752
	s_add_i32 s98, s98, 0x3000
	s_cmp_eq_u32 s98, 0xc000
	s_cselect_b32 s98, 0, s98
	s_add_i32 s99, s99, 0x3000
	s_cmp_eq_u32 s99, 0xc000
	s_cselect_b32 s99, 0, s99
	s_add_i32 s100, s100, 0x2000
	s_cmp_eq_u32 s100, 0xc000
	s_cselect_b32 s100, 0, s100
	s_add_i32 s101, s101, 0x2000
	s_cmp_eq_u32 s101, 0xc000
	s_cselect_b32 s101, 0, s101
	s_cmp_gt_u32 s6, 60
	s_cbranch_scc1 .Lwl_b
	s_and_b64 vcc, exec, s[56:57]
	s_cbranch_vccnz .Lwh_b
	s_waitcnt vmcnt(6) lgkmcnt(0)
	s_branch .Lwd_b

; __device__ __forceinline__ void finishSM2(f32x16& p0, f32x16& p1, float alpha, float& l_reg, bf16x8& pa0, bf16x8& pa1, bf16x8& pa2, bf16x8& pa3) {
; #pragma unroll
;   for (int r = 0; r < 16; ++r) p1[r] = __builtin_amdgcn_exp2f(p1[r]);
;   float ps = 0;
; #pragma unroll
;   for (int r = 0; r < 16; ++r) ps += p0[r];
; #pragma unroll
;   for (int r = 0; r < 16; ++r) ps += p1[r];
;   { auto rr = __builtin_amdgcn_permlane32_swap(__float_as_uint(ps), __float_as_uint(ps), false, false);
;     ps = __uint_as_float(rr[0]) + __uint_as_float(rr[1]); }
;   l_reg = l_reg * alpha + ps;
;     ...
;   PK8(p0, 0, pa0); PK8(p0, 8, pa1); PK8(p1, 0, pa2); PK8(p1, 8, pa3);
;     ...
; }
; __device__ __forceinline__ void kload12(bf16x8* kf, const LAS char* Ks, int r32, int hi) {
;   const LAS char* kb = Ks + hi * 1024 + r32 * 16;
; #pragma unroll
;   for (int d0 = 0; d0 < 6; ++d0) { kf[2 * d0] = *(const LAS bf16x8*)(kb + d0 * 2048); kf[2 * d0 + 1] = *(const LAS bf16x8*)(kb + d0 * 2048 + 512); }
; }
; __device__ __forceinline__ void qkt3(f32x16& p0, f32x16& p1, const bf16x8* kf, const bf16x8* qr) {
;   p0 = f32x16{}; p1 = f32x16{};
; #pragma unroll
;   for (int d0 = 0; d0 < 6; ++d0) {
;     p0 = __builtin_amdgcn_mfma_f32_32x32x16_bf16(kf[2 * d0], qr[d0], p0, 0, 0, 0);
;     p1 = __builtin_amdgcn_mfma_f32_32x32x16_bf16(kf[2 * d0 + 1], qr[d0], p1, 0, 0, 0); }
; }
; __device__ __forceinline__ void vload16(s16x4* vf, int vb) {
;   vf[0] = tr_read<0>(vb); vf[1] = tr_read<512>(vb); vf[2] = tr_read<1024>(vb); vf[3] = tr_read<1536>(vb);
;   vf[4] = tr_read<2048>(vb); vf[5] = tr_read<2560>(vb); vf[6] = tr_read<3072>(vb); vf[7] = tr_read<3584>(vb);
;   vf[8] = tr_read<4096>(vb); vf[9] = tr_read<4608>(vb); vf[10] = tr_read<5120>(vb); vf[11] = tr_read<5632>(vb);
;   vf[12] = tr_read<6144>(vb); vf[13] = tr_read<6656>(vb); vf[14] = tr_read<7168>(vb); vf[15] = tr_read<7680>(vb);
; }
; __device__ __forceinline__ void pv3(f32x16* o, const s16x4* vf, bf16x8 pa0, bf16x8 pa1, bf16x8 pa2, bf16x8 pa3) {
;     ...
;   o[0] = __builtin_amdgcn_mfma_f32_32x32x16_bf16(pa0, PKV(0), o[0], 0, 0, 0);
;   o[1] = __builtin_amdgcn_mfma_f32_32x32x16_bf16(pa0, PKV(8), o[1], 0, 0, 0);
;   o[0] = __builtin_amdgcn_mfma_f32_32x32x16_bf16(pa1, PKV(2), o[0], 0, 0, 0);
;   o[1] = __builtin_amdgcn_mfma_f32_32x32x16_bf16(pa1, PKV(10), o[1], 0, 0, 0);
;   o[0] = __builtin_amdgcn_mfma_f32_32x32x16_bf16(pa2, PKV(4), o[0], 0, 0, 0);
.Lwl_b:
	s_waitcnt vmcnt(0) lgkmcnt(0)
.Lwd_b:
	s_barrier
	s_waitcnt lgkmcnt(0)
	v_mfma_f32_32x32x16_bf16 v[80:95], v[246:249], v[248:251], 0
	v_exp_f32_e32 v48, v48
	v_add_f32_e32 v213, v32, v213
	ds_read_b64_tr_b16 v[148:149], v217 offset:0
	v_exp_f32_e32 v49, v49
	v_add_f32_e32 v213, v33, v213
	ds_read_b64_tr_b16 v[150:151], v217 offset:512
	v_mfma_f32_32x32x16_bf16 v[80:95], v[64:67], v[116:119], v[80:95]
	v_exp_f32_e32 v50, v50
	v_add_f32_e32 v213, v34, v213
	ds_read_b64_tr_b16 v[140:141], v217 offset:1024
	v_exp_f32_e32 v51, v51
	v_add_f32_e32 v213, v35, v213
	ds_read_b64_tr_b16 v[142:143], v217 offset:1536
	v_mfma_f32_32x32x16_bf16 v[64:79], v[68:71], v[116:119], 0
	v_exp_f32_e32 v52, v52
	v_add_f32_e32 v213, v36, v213
	ds_read_b64_tr_b16 v[132:133], v217 offset:2048
	v_exp_f32_e32 v53, v53
	v_add_f32_e32 v213, v37, v213
	ds_read_b64_tr_b16 v[134:135], v217 offset:2560
	v_mfma_f32_32x32x16_bf16 v[64:79], v[246:249], v[248:251], v[64:79]
	v_exp_f32_e32 v54, v54
	v_add_f32_e32 v213, v38, v213
	ds_read_b64_tr_b16 v[124:125], v217 offset:3072
	v_exp_f32_e32 v55, v55
	v_add_f32_e32 v213, v39, v213
	ds_read_b64_tr_b16 v[126:127], v217 offset:3584
	v_mfma_f32_32x32x16_bf16 v[80:95], v[188:191], v[112:115], v[80:95]
	v_exp_f32_e32 v56, v56
	v_add_f32_e32 v213, v40, v213
	ds_read_b64_tr_b16 v[144:145], v217 offset:4096
	v_exp_f32_e32 v57, v57
	v_add_f32_e32 v213, v41, v213
	ds_read_b64_tr_b16 v[146:147], v217 offset:4608
	v_mfma_f32_32x32x16_bf16 v[64:79], v[184:187], v[112:115], v[64:79]
	v_exp_f32_e32 v58, v58
	v_add_f32_e32 v213, v42, v213
	ds_read_b64_tr_b16 v[136:137], v217 offset:5120
	v_exp_f32_e32 v59, v59
	v_add_f32_e32 v213, v43, v213
	ds_read_b64_tr_b16 v[138:139], v217 offset:5632
	v_mfma_f32_32x32x16_bf16 v[80:95], v[180:183], v[108:111], v[80:95]
	v_exp_f32_e32 v60, v60
	v_add_f32_e32 v213, v44, v213
	ds_read_b64_tr_b16 v[128:129], v217 offset:6144
	v_exp_f32_e32 v61, v61
	v_add_f32_e32 v213, v45, v213
	ds_read_b64_tr_b16 v[130:131], v217 offset:6656
	v_mfma_f32_32x32x16_bf16 v[64:79], v[176:179], v[108:111], v[64:79]
	v_exp_f32_e32 v62, v62
	v_add_f32_e32 v213, v46, v213
	ds_read_b64_tr_b16 v[120:121], v217 offset:7168
	v_exp_f32_e32 v63, v63
	v_add_f32_e32 v213, v47, v213
	ds_read_b64_tr_b16 v[122:123], v217 offset:7680
	v_mfma_f32_32x32x16_bf16 v[80:95], v[172:175], v[104:107], v[80:95]
	v_add_f32_e32 v245, v48, v49
	v_add_f32_e32 v245, v50, v245
	v_add_f32_e32 v245, v51, v245
	v_add_f32_e32 v245, v52, v245
	v_add_f32_e32 v245, v53, v245
	v_add_f32_e32 v245, v54, v245
	v_mfma_f32_32x32x16_bf16 v[64:79], v[168:171], v[104:107], v[64:79]
	v_add_f32_e32 v245, v55, v245
	v_add_f32_e32 v245, v56, v245
	v_add_f32_e32 v245, v57, v245
	v_add_f32_e32 v245, v58, v245
	v_add_f32_e32 v245, v59, v245
	v_mfma_f32_32x32x16_bf16 v[80:95], v[164:167], v[100:103], v[80:95]
	v_add_f32_e32 v245, v60, v245
	v_add_f32_e32 v245, v61, v245
	v_add_f32_e32 v245, v62, v245
	v_add_f32_e32 v245, v63, v245
	v_add_f32_e32 v213, v245, v213
	v_mfma_f32_32x32x16_bf16 v[64:79], v[160:163], v[100:103], v[64:79]
	v_cvt_pk_bf16_f32 v32, v32, v33
	v_cvt_pk_bf16_f32 v33, v34, v35
	v_cvt_pk_bf16_f32 v34, v36, v37
	v_cvt_pk_bf16_f32 v35, v38, v39
	v_cvt_pk_bf16_f32 v36, v40, v41
	v_cvt_pk_bf16_f32 v37, v42, v43
	v_mfma_f32_32x32x16_bf16 v[80:95], v[156:159], v[96:99], v[80:95]
	v_cvt_pk_bf16_f32 v38, v44, v45
	v_cvt_pk_bf16_f32 v39, v46, v47
	v_cvt_pk_bf16_f32 v48, v48, v49
	v_cvt_pk_bf16_f32 v49, v50, v51
	v_cvt_pk_bf16_f32 v50, v52, v53
	v_cvt_pk_bf16_f32 v51, v54, v55
	v_mfma_f32_32x32x16_bf16 v[64:79], v[152:155], v[96:99], v[64:79]
	v_cvt_pk_bf16_f32 v52, v56, v57
	v_cvt_pk_bf16_f32 v53, v58, v59
	v_cvt_pk_bf16_f32 v54, v60, v61
	v_cvt_pk_bf16_f32 v55, v62, v63
	s_waitcnt lgkmcnt(0)
	v_mfma_f32_32x32x16_bf16 v[0:15], v[32:35], v[148:151], v[0:15]
	v_exp_f32_e32 v40, v88
	v_exp_f32_e32 v41, v89
	v_max3_f32 v252, v80, v81, v82
	v_mfma_f32_32x32x16_bf16 v[16:31], v[32:35], v[144:147], v[16:31]
	v_exp_f32_e32 v42, v90
	v_exp_f32_e32 v43, v91
	v_max3_f32 v252, v252, v83, v84
	v_max3_f32 v252, v252, v85, v86
	v_mfma_f32_32x32x16_bf16 v[0:15], v[36:39], v[140:143], v[0:15]
	v_exp_f32_e32 v44, v92
	v_exp_f32_e32 v45, v93
	v_max3_f32 v252, v252, v87, v88
	v_max3_f32 v252, v252, v89, v90
	v_mfma_f32_32x32x16_bf16 v[16:31], v[36:39], v[136:139], v[16:31]
	v_exp_f32_e32 v46, v94
	v_exp_f32_e32 v47, v95
	v_max3_f32 v252, v252, v91, v92
	v_max3_f32 v252, v252, v93, v94
	v_mfma_f32_32x32x16_bf16 v[0:15], v[48:51], v[132:135], v[0:15]
	v_exp_f32_e32 v32, v80
	v_exp_f32_e32 v33, v81
	v_max3_f32 v252, v252, v95, v64
	v_max3_f32 v252, v252, v65, v66
	v_mfma_f32_32x32x16_bf16 v[16:31], v[48:51], v[128:131], v[16:31]
	v_exp_f32_e32 v34, v82
	v_exp_f32_e32 v35, v83
	v_max3_f32 v252, v252, v67, v68
	v_max3_f32 v252, v252, v69, v70
	v_mfma_f32_32x32x16_bf16 v[0:15], v[52:55], v[124:127], v[0:15]
	v_exp_f32_e32 v36, v84
	v_exp_f32_e32 v37, v85
	v_max3_f32 v252, v252, v71, v72
	v_max3_f32 v252, v252, v73, v74
	v_mfma_f32_32x32x16_bf16 v[16:31], v[52:55], v[120:123], v[16:31]
	v_max3_f32 v252, v252, v75, v76
	v_max3_f32 v252, v252, v77, v78
	v_max_f32_e32 v252, v252, v79
	v_cmp_nge_f32_e32 vcc, s23, v252
	v_exp_f32_e32 v38, v86
	v_exp_f32_e32 v39, v87
	s_nop 0
	s_cmp_lg_u64 vcc, 0
	s_cbranch_scc1 .Lrare_b

; template <int MODE> __device__ __forceinline__ void attn_unit(const bf16_t* __restrict__ Q, const bf16_t* __restrict__ KV, const bf16_t* __restrict__ KR, bf16_t* __restrict__ O,
;                                           long rowbase, int q0, int h, LAS char* lds) {
;     ...
;   for (int j = 1; j + 1 < NT; j += 2) {
;     STEP(j, pB0, pB1, mnB, alB, pA0, pA1, alA);
;     STEP(j + 1, pA0, pA1, mnA, alA, pB0, pB1, alB);
;   }
;   STEP(NT - 1, pB0, pB1, mnB, alB, pA0, pA1, alA);
.LBB0_597:
	ds_read_b128 v[48:51], v231 offset:36864
	ds_read_b128 v[52:55], v231 offset:37376
	ds_read_b128 v[188:191], v231 offset:38912
	ds_read_b128 v[184:187], v231 offset:39424
	ds_read_b128 v[180:183], v231 offset:40960
	ds_read_b128 v[176:179], v231 offset:41472
	ds_read_b128 v[172:175], v231 offset:43008
	ds_read_b128 v[168:171], v231 offset:43520
	ds_read_b128 v[164:167], v231 offset:45056
	ds_read_b128 v[160:163], v231 offset:45568
	ds_read_b128 v[156:159], v231 offset:47104
	ds_read_b128 v[152:155], v231 offset:47616
	s_waitcnt vmcnt(0) lgkmcnt(0)
	s_barrier
	s_waitcnt lgkmcnt(0)
	v_mfma_f32_32x32x16_bf16 v[80:95], v[246:249], v[248:251], 0
	v_exp_f32_e32 v64, v64
	v_add_f32_e32 v213, v32, v213
	ds_read_b64_tr_b16 v[148:149], v233 offset:0
	v_exp_f32_e32 v65, v65
	v_add_f32_e32 v213, v33, v213
	ds_read_b64_tr_b16 v[150:151], v233 offset:512
	v_mfma_f32_32x32x16_bf16 v[80:95], v[48:51], v[116:119], v[80:95]
	v_exp_f32_e32 v66, v66
	v_add_f32_e32 v213, v34, v213
	ds_read_b64_tr_b16 v[140:141], v233 offset:1024
	v_exp_f32_e32 v67, v67
	v_add_f32_e32 v213, v35, v213
	ds_read_b64_tr_b16 v[142:143], v233 offset:1536
	v_mfma_f32_32x32x16_bf16 v[48:63], v[52:55], v[116:119], 0
	v_exp_f32_e32 v68, v68
	v_add_f32_e32 v213, v36, v213
	ds_read_b64_tr_b16 v[132:133], v233 offset:2048
	v_exp_f32_e32 v69, v69
	v_add_f32_e32 v213, v37, v213
	ds_read_b64_tr_b16 v[134:135], v233 offset:2560
	v_mfma_f32_32x32x16_bf16 v[48:63], v[246:249], v[248:251], v[48:63]
	v_exp_f32_e32 v70, v70
	v_add_f32_e32 v213, v38, v213
	ds_read_b64_tr_b16 v[124:125], v233 offset:3072
	v_exp_f32_e32 v71, v71
	v_add_f32_e32 v213, v39, v213
	ds_read_b64_tr_b16 v[126:127], v233 offset:3584
	v_mfma_f32_32x32x16_bf16 v[80:95], v[188:191], v[112:115], v[80:95]
	v_exp_f32_e32 v72, v72
	v_add_f32_e32 v213, v40, v213
	ds_read_b64_tr_b16 v[144:145], v233 offset:4096
	v_exp_f32_e32 v73, v73
	v_add_f32_e32 v213, v41, v213
	ds_read_b64_tr_b16 v[146:147], v233 offset:4608
	v_mfma_f32_32x32x16_bf16 v[48:63], v[184:187], v[112:115], v[48:63]
	v_exp_f32_e32 v74, v74
	v_add_f32_e32 v213, v42, v213
	ds_read_b64_tr_b16 v[136:137], v233 offset:5120
	v_exp_f32_e32 v75, v75
	v_add_f32_e32 v213, v43, v213
	ds_read_b64_tr_b16 v[138:139], v233 offset:5632
	v_mfma_f32_32x32x16_bf16 v[80:95], v[180:183], v[108:111], v[80:95]
	v_exp_f32_e32 v76, v76
	v_add_f32_e32 v213, v44, v213
	ds_read_b64_tr_b16 v[128:129], v233 offset:6144
	v_exp_f32_e32 v77, v77
	v_add_f32_e32 v213, v45, v213
	ds_read_b64_tr_b16 v[130:131], v233 offset:6656
	v_mfma_f32_32x32x16_bf16 v[48:63], v[176:179], v[108:111], v[48:63]
	v_exp_f32_e32 v78, v78
	v_add_f32_e32 v213, v46, v213
	ds_read_b64_tr_b16 v[120:121], v233 offset:7168
	v_exp_f32_e32 v79, v79
	v_add_f32_e32 v213, v47, v213
	ds_read_b64_tr_b16 v[122:123], v233 offset:7680
	v_mfma_f32_32x32x16_bf16 v[80:95], v[172:175], v[104:107], v[80:95]
	v_add_f32_e32 v245, v64, v65
	v_add_f32_e32 v245, v66, v245
	v_add_f32_e32 v245, v67, v245
	v_add_f32_e32 v245, v68, v245
	v_add_f32_e32 v245, v69, v245
	v_add_f32_e32 v245, v70, v245
	v_mfma_f32_32x32x16_bf16 v[48:63], v[168:171], v[104:107], v[48:63]
	v_add_f32_e32 v245, v71, v245
	v_add_f32_e32 v245, v72, v245
	v_add_f32_e32 v245, v73, v245
	v_add_f32_e32 v245, v74, v245
	v_add_f32_e32 v245, v75, v245
	v_mfma_f32_32x32x16_bf16 v[80:95], v[164:167], v[100:103], v[80:95]
	v_add_f32_e32 v245, v76, v245
	v_add_f32_e32 v245, v77, v245
	v_add_f32_e32 v245, v78, v245
	v_add_f32_e32 v245, v79, v245
	v_add_f32_e32 v213, v245, v213
	v_mfma_f32_32x32x16_bf16 v[48:63], v[160:163], v[100:103], v[48:63]
	v_cvt_pk_bf16_f32 v32, v32, v33
	v_cvt_pk_bf16_f32 v33, v34, v35
	v_cvt_pk_bf16_f32 v34, v36, v37
	v_cvt_pk_bf16_f32 v35, v38, v39
	v_cvt_pk_bf16_f32 v36, v40, v41
	v_cvt_pk_bf16_f32 v37, v42, v43
	v_mfma_f32_32x32x16_bf16 v[80:95], v[156:159], v[96:99], v[80:95]
	v_cvt_pk_bf16_f32 v38, v44, v45
	v_cvt_pk_bf16_f32 v39, v46, v47
	v_cvt_pk_bf16_f32 v64, v64, v65
	v_cvt_pk_bf16_f32 v65, v66, v67
	v_cvt_pk_bf16_f32 v66, v68, v69
	v_cvt_pk_bf16_f32 v67, v70, v71
	v_mfma_f32_32x32x16_bf16 v[48:63], v[152:155], v[96:99], v[48:63]
	v_cvt_pk_bf16_f32 v68, v72, v73
	v_cvt_pk_bf16_f32 v69, v74, v75
	v_cvt_pk_bf16_f32 v70, v76, v77
	v_cvt_pk_bf16_f32 v71, v78, v79
	s_waitcnt lgkmcnt(0)
	v_mfma_f32_32x32x16_bf16 v[0:15], v[32:35], v[148:151], v[0:15]
	v_exp_f32_e32 v40, v88
	v_exp_f32_e32 v41, v89
	v_max3_f32 v252, v80, v81, v82
	v_mfma_f32_32x32x16_bf16 v[16:31], v[32:35], v[144:147], v[16:31]
	v_exp_f32_e32 v42, v90
	v_exp_f32_e32 v43, v91
	v_max3_f32 v252, v252, v83, v84
	v_max3_f32 v252, v252, v85, v86
	v_mfma_f32_32x32x16_bf16 v[0:15], v[36:39], v[140:143], v[0:15]
	v_exp_f32_e32 v44, v92
	v_exp_f32_e32 v45, v93
	v_max3_f32 v252, v252, v87, v88
	v_max3_f32 v252, v252, v89, v90
	v_mfma_f32_32x32x16_bf16 v[16:31], v[36:39], v[136:139], v[16:31]
	v_exp_f32_e32 v46, v94
	v_exp_f32_e32 v47, v95
	v_max3_f32 v252, v252, v91, v92
	v_max3_f32 v252, v252, v93, v94
	v_mfma_f32_32x32x16_bf16 v[0:15], v[64:67], v[132:135], v[0:15]
	v_exp_f32_e32 v32, v80
	v_exp_f32_e32 v33, v81
	v_max3_f32 v252, v252, v95, v48
	v_max3_f32 v252, v252, v49, v50
	v_mfma_f32_32x32x16_bf16 v[16:31], v[64:67], v[128:131], v[16:31]
	v_exp_f32_e32 v34, v82
	v_exp_f32_e32 v35, v83
	v_max3_f32 v252, v252, v51, v52
	v_max3_f32 v252, v252, v53, v54
	v_mfma_f32_32x32x16_bf16 v[0:15], v[68:71], v[124:127], v[0:15]
	v_exp_f32_e32 v36, v84
	v_exp_f32_e32 v37, v85
	v_max3_f32 v252, v252, v55, v56
	v_max3_f32 v252, v252, v57, v58
	v_mfma_f32_32x32x16_bf16 v[16:31], v[68:71], v[120:123], v[16:31]
	v_max3_f32 v252, v252, v59, v60
	v_max3_f32 v252, v252, v61, v62
	v_max_f32_e32 v252, v252, v63
	v_cmp_nge_f32_e32 vcc, s23, v252
	v_exp_f32_e32 v38, v86
	v_exp_f32_e32 v39, v87
	s_nop 0
	s_cmp_lg_u64 vcc, 0
	s_cbranch_scc1 .Lrare_t

; #define FMA_S(x) asm("v_fma_f32 %0, %1, %2, %3" : "=v"(x) : "v"(x), "v"(Cv), "v"(mnC))
; __device__ __forceinline__ void partialSM(f32x16& p0, f32x16& p1, float& m_reg, float& mn, float& alpha) {
;     ...
;   if (__builtin_expect(__all(pmax - m_reg <= THR / SCALE), 1)) { mn = m_reg; alpha = 1.f; }
;   else { mn = fmaxf(m_reg, pmax); alpha = __builtin_amdgcn_exp2f((m_reg - mn) * C); m_reg = mn; }
;   const float mnC = -mn * C;
;     ...
;   float Cv = C; asm volatile("" : "+v"(Cv));
; #pragma unroll
;   for (int r = 0; r < 16; ++r) FMA_S(p0[r]);
; #pragma unroll
;   for (int r = 0; r < 16; ++r) FMA_S(p1[r]);
.Lrare_a:
	v_mov_b32_e32 v253, v252
	s_nop 1
	v_permlane32_swap_b32_e32 v252, v253
	v_max_f32_e32 v252, v252, v253
	v_max_f32_e32 v252, 0, v252
	v_lshlrev_b32_e32 v253, 16, v251
	v_sub_f32_e32 v255, v252, v253
	v_and_b32_e32 v255, 0xffff0000, v255
	v_add_f32_e32 v152, v255, v253
	v_xor_b32_e32 v255, 0x80000000, v255
	v_lshrrev_b32_e32 v251, 16, v255
	v_sub_f32_e32 v153, 0, v152
	v_exp_f32_e32 v153, v153
	v_sub_f32_e32 v48, v48, v152
	v_sub_f32_e32 v49, v49, v152
	v_sub_f32_e32 v50, v50, v152
	v_sub_f32_e32 v51, v51, v152
	v_sub_f32_e32 v52, v52, v152
	v_sub_f32_e32 v53, v53, v152
	v_sub_f32_e32 v54, v54, v152
	v_sub_f32_e32 v55, v55, v152
	v_sub_f32_e32 v56, v56, v152
	v_sub_f32_e32 v57, v57, v152
	v_sub_f32_e32 v58, v58, v152
	v_sub_f32_e32 v59, v59, v152
	v_sub_f32_e32 v60, v60, v152
	v_sub_f32_e32 v61, v61, v152
	v_sub_f32_e32 v62, v62, v152
	v_sub_f32_e32 v63, v63, v152
	v_mul_f32_e32 v213, v213, v153
	v_sub_f32_e32 v154, v80, v152
	v_sub_f32_e32 v253, v81, v152
	v_exp_f32_e32 v32, v154
	v_sub_f32_e32 v154, v82, v152
	v_exp_f32_e32 v33, v253
	v_sub_f32_e32 v253, v83, v152
	v_exp_f32_e32 v34, v154
	v_sub_f32_e32 v154, v84, v152
	v_exp_f32_e32 v35, v253
	v_sub_f32_e32 v253, v85, v152
	v_exp_f32_e32 v36, v154
	v_sub_f32_e32 v154, v86, v152
	v_exp_f32_e32 v37, v253
	v_sub_f32_e32 v253, v87, v152
	v_exp_f32_e32 v38, v154
	v_sub_f32_e32 v154, v88, v152
	v_exp_f32_e32 v39, v253
	v_sub_f32_e32 v253, v89, v152
	v_exp_f32_e32 v40, v154
	v_sub_f32_e32 v154, v90, v152
	v_exp_f32_e32 v41, v253
	v_sub_f32_e32 v253, v91, v152
	v_exp_f32_e32 v42, v154
	v_sub_f32_e32 v154, v92, v152
	v_exp_f32_e32 v43, v253
	v_sub_f32_e32 v253, v93, v152
	v_exp_f32_e32 v44, v154
	v_sub_f32_e32 v154, v94, v152
	v_exp_f32_e32 v45, v253
	v_sub_f32_e32 v253, v95, v152
	v_exp_f32_e32 v46, v154
	v_exp_f32_e32 v47, v253
	s_nop 0
	s_and_saveexec_b64 s[58:59], s[2:3]
	ds_write_b32 v211, v153 offset:128
	s_or_b64 exec, exec, s[58:59]
	s_waitcnt lgkmcnt(0)
	v_add_u32_e32 v245, s62, v232
	ds_read_b128 v[80:83], v245 offset:224
	ds_read_b128 v[84:87], v245 offset:192
	ds_read_b128 v[88:91], v245 offset:160
	ds_read_b128 v[92:95], v245 offset:128
	s_waitcnt lgkmcnt(0)
	v_pk_mul_f32 v[12:13], v[12:13], v[80:81]
	v_pk_mul_f32 v[8:9], v[8:9], v[84:85]
	v_pk_mul_f32 v[4:5], v[4:5], v[88:89]
	v_pk_mul_f32 v[14:15], v[14:15], v[82:83]
	v_pk_mul_f32 v[10:11], v[10:11], v[86:87]
	v_pk_mul_f32 v[6:7], v[6:7], v[90:91]
	v_pk_mul_f32 v[2:3], v[2:3], v[94:95]
	v_pk_mul_f32 v[0:1], v[0:1], v[92:93]
	v_pk_mul_f32 v[28:29], v[28:29], v[80:81]
	v_pk_mul_f32 v[24:25], v[24:25], v[84:85]
	v_pk_mul_f32 v[20:21], v[20:21], v[88:89]
	v_pk_mul_f32 v[30:31], v[30:31], v[82:83]
	v_pk_mul_f32 v[26:27], v[26:27], v[86:87]
	v_pk_mul_f32 v[22:23], v[22:23], v[90:91]
	v_pk_mul_f32 v[18:19], v[18:19], v[94:95]
	v_pk_mul_f32 v[16:17], v[16:17], v[92:93]
	s_branch .Ljoin_a
; #define FMA_S(x) asm("v_fma_f32 %0, %1, %2, %3" : "=v"(x) : "v"(x), "v"(Cv), "v"(mnC))
; __device__ __forceinline__ void partialSM(f32x16& p0, f32x16& p1, float& m_reg, float& mn, float& alpha) {
;     ...
;   if (__builtin_expect(__all(pmax - m_reg <= THR / SCALE), 1)) { mn = m_reg; alpha = 1.f; }
;   else { mn = fmaxf(m_reg, pmax); alpha = __builtin_amdgcn_exp2f((m_reg - mn) * C); m_reg = mn; }
;   const float mnC = -mn * C;
;     ...
;   float Cv = C; asm volatile("" : "+v"(Cv));
; #pragma unroll
;   for (int r = 0; r < 16; ++r) FMA_S(p0[r]);
; #pragma unroll
;   for (int r = 0; r < 16; ++r) FMA_S(p1[r]);
.Lrare_b:
	v_mov_b32_e32 v253, v252
	s_nop 1
	v_permlane32_swap_b32_e32 v252, v253
	v_max_f32_e32 v252, v252, v253
	v_max_f32_e32 v252, 0, v252
	v_lshlrev_b32_e32 v253, 16, v251
	v_sub_f32_e32 v255, v252, v253
	v_and_b32_e32 v255, 0xffff0000, v255
	v_add_f32_e32 v152, v255, v253
	v_xor_b32_e32 v255, 0x80000000, v255
	v_lshrrev_b32_e32 v251, 16, v255
	v_sub_f32_e32 v153, 0, v152
	v_exp_f32_e32 v153, v153
	v_sub_f32_e32 v64, v64, v152
	v_sub_f32_e32 v65, v65, v152
	v_sub_f32_e32 v66, v66, v152
	v_sub_f32_e32 v67, v67, v152
	v_sub_f32_e32 v68, v68, v152
	v_sub_f32_e32 v69, v69, v152
	v_sub_f32_e32 v70, v70, v152
	v_sub_f32_e32 v71, v71, v152
	v_sub_f32_e32 v72, v72, v152
	v_sub_f32_e32 v73, v73, v152
	v_sub_f32_e32 v74, v74, v152
	v_sub_f32_e32 v75, v75, v152
	v_sub_f32_e32 v76, v76, v152
	v_sub_f32_e32 v77, v77, v152
	v_sub_f32_e32 v78, v78, v152
	v_sub_f32_e32 v79, v79, v152
	v_mul_f32_e32 v213, v213, v153
	v_sub_f32_e32 v154, v80, v152
	v_sub_f32_e32 v253, v81, v152
	v_exp_f32_e32 v32, v154
	v_sub_f32_e32 v154, v82, v152
	v_exp_f32_e32 v33, v253
	v_sub_f32_e32 v253, v83, v152
	v_exp_f32_e32 v34, v154
	v_sub_f32_e32 v154, v84, v152
	v_exp_f32_e32 v35, v253
	v_sub_f32_e32 v253, v85, v152
	v_exp_f32_e32 v36, v154
	v_sub_f32_e32 v154, v86, v152
	v_exp_f32_e32 v37, v253
	v_sub_f32_e32 v253, v87, v152
	v_exp_f32_e32 v38, v154
	v_sub_f32_e32 v154, v88, v152
	v_exp_f32_e32 v39, v253
	v_sub_f32_e32 v253, v89, v152
	v_exp_f32_e32 v40, v154
	v_sub_f32_e32 v154, v90, v152
	v_exp_f32_e32 v41, v253
	v_sub_f32_e32 v253, v91, v152
	v_exp_f32_e32 v42, v154
	v_sub_f32_e32 v154, v92, v152
	v_exp_f32_e32 v43, v253
	v_sub_f32_e32 v253, v93, v152
	v_exp_f32_e32 v44, v154
	v_sub_f32_e32 v154, v94, v152
	v_exp_f32_e32 v45, v253
	v_sub_f32_e32 v253, v95, v152
	v_exp_f32_e32 v46, v154
	v_exp_f32_e32 v47, v253
	s_nop 0
	s_and_saveexec_b64 s[60:61], s[2:3]
	ds_write_b32 v211, v153 offset:128
	s_or_b64 exec, exec, s[60:61]
	s_waitcnt lgkmcnt(0)
	v_add_u32_e32 v245, s62, v232
	ds_read_b128 v[80:83], v245 offset:224
	ds_read_b128 v[84:87], v245 offset:192
	ds_read_b128 v[88:91], v245 offset:160
	ds_read_b128 v[92:95], v245 offset:128
	s_waitcnt lgkmcnt(0)
	v_pk_mul_f32 v[12:13], v[12:13], v[80:81]
	v_pk_mul_f32 v[8:9], v[8:9], v[84:85]
	v_pk_mul_f32 v[4:5], v[4:5], v[88:89]
	v_pk_mul_f32 v[14:15], v[14:15], v[82:83]
	v_pk_mul_f32 v[10:11], v[10:11], v[86:87]
	v_pk_mul_f32 v[6:7], v[6:7], v[90:91]
	v_pk_mul_f32 v[2:3], v[2:3], v[94:95]
	v_pk_mul_f32 v[0:1], v[0:1], v[92:93]
	v_pk_mul_f32 v[28:29], v[28:29], v[80:81]
	v_pk_mul_f32 v[24:25], v[24:25], v[84:85]
	v_pk_mul_f32 v[20:21], v[20:21], v[88:89]
	v_pk_mul_f32 v[30:31], v[30:31], v[82:83]
	v_pk_mul_f32 v[26:27], v[26:27], v[86:87]
	v_pk_mul_f32 v[22:23], v[22:23], v[90:91]
	v_pk_mul_f32 v[18:19], v[18:19], v[94:95]
	v_pk_mul_f32 v[16:17], v[16:17], v[92:93]
	s_branch .Ljoin_b
.Lrare_t:
	v_mov_b32_e32 v253, v252
	s_nop 1
	v_permlane32_swap_b32_e32 v252, v253
	v_max_f32_e32 v252, v252, v253
	v_max_f32_e32 v252, 0, v252
	v_lshlrev_b32_e32 v253, 16, v251
	v_sub_f32_e32 v255, v252, v253
	v_and_b32_e32 v255, 0xffff0000, v255
	v_add_f32_e32 v152, v255, v253
	v_xor_b32_e32 v255, 0x80000000, v255
	v_lshrrev_b32_e32 v251, 16, v255
	v_sub_f32_e32 v153, 0, v152
	v_exp_f32_e32 v153, v153
	v_sub_f32_e32 v48, v48, v152
	v_sub_f32_e32 v49, v49, v152
	v_sub_f32_e32 v50, v50, v152
	v_sub_f32_e32 v51, v51, v152
	v_sub_f32_e32 v52, v52, v152
	v_sub_f32_e32 v53, v53, v152
	v_sub_f32_e32 v54, v54, v152
	v_sub_f32_e32 v55, v55, v152
	v_sub_f32_e32 v56, v56, v152
	v_sub_f32_e32 v57, v57, v152
	v_sub_f32_e32 v58, v58, v152
	v_sub_f32_e32 v59, v59, v152
	v_sub_f32_e32 v60, v60, v152
	v_sub_f32_e32 v61, v61, v152
	v_sub_f32_e32 v62, v62, v152
	v_sub_f32_e32 v63, v63, v152
	v_mul_f32_e32 v213, v213, v153
	v_sub_f32_e32 v154, v80, v152
	v_sub_f32_e32 v253, v81, v152
	v_exp_f32_e32 v32, v154
	v_sub_f32_e32 v154, v82, v152
	v_exp_f32_e32 v33, v253
	v_sub_f32_e32 v253, v83, v152
	v_exp_f32_e32 v34, v154
	v_sub_f32_e32 v154, v84, v152
	v_exp_f32_e32 v35, v253
	v_sub_f32_e32 v253, v85, v152
	v_exp_f32_e32 v36, v154
	v_sub_f32_e32 v154, v86, v152
	v_exp_f32_e32 v37, v253
	v_sub_f32_e32 v253, v87, v152
	v_exp_f32_e32 v38, v154
	v_sub_f32_e32 v154, v88, v152
	v_exp_f32_e32 v39, v253
	v_sub_f32_e32 v253, v89, v152
	v_exp_f32_e32 v40, v154
	v_sub_f32_e32 v154, v90, v152
	v_exp_f32_e32 v41, v253
	v_sub_f32_e32 v253, v91, v152
	v_exp_f32_e32 v42, v154
	v_sub_f32_e32 v154, v92, v152
	v_exp_f32_e32 v43, v253
	v_sub_f32_e32 v253, v93, v152
	v_exp_f32_e32 v44, v154
	v_sub_f32_e32 v154, v94, v152
	v_exp_f32_e32 v45, v253
	v_sub_f32_e32 v253, v95, v152
	v_exp_f32_e32 v46, v154
	v_exp_f32_e32 v47, v253
	s_nop 0
	s_and_saveexec_b64 s[56:57], s[2:3]
	ds_write_b32 v211, v153 offset:128
	s_or_b64 exec, exec, s[56:57]
	s_waitcnt lgkmcnt(0)
	v_add_u32_e32 v245, s62, v232
	ds_read_b128 v[80:83], v245 offset:224
	ds_read_b128 v[84:87], v245 offset:192
	ds_read_b128 v[88:91], v245 offset:160
	ds_read_b128 v[92:95], v245 offset:128
	s_waitcnt lgkmcnt(0)
	v_pk_mul_f32 v[12:13], v[12:13], v[80:81]
	v_pk_mul_f32 v[8:9], v[8:9], v[84:85]
	v_pk_mul_f32 v[4:5], v[4:5], v[88:89]
	v_pk_mul_f32 v[14:15], v[14:15], v[82:83]
	v_pk_mul_f32 v[10:11], v[10:11], v[86:87]
	v_pk_mul_f32 v[6:7], v[6:7], v[90:91]
	v_pk_mul_f32 v[2:3], v[2:3], v[94:95]
	v_pk_mul_f32 v[0:1], v[0:1], v[92:93]
	v_pk_mul_f32 v[28:29], v[28:29], v[80:81]
	v_pk_mul_f32 v[24:25], v[24:25], v[84:85]
	v_pk_mul_f32 v[20:21], v[20:21], v[88:89]
	v_pk_mul_f32 v[30:31], v[30:31], v[82:83]
	v_pk_mul_f32 v[26:27], v[26:27], v[86:87]
	v_pk_mul_f32 v[22:23], v[22:23], v[90:91]
	v_pk_mul_f32 v[18:19], v[18:19], v[94:95]
	v_pk_mul_f32 v[16:17], v[16:17], v[92:93]
	s_branch .Ljoin_t

; __global__ void __launch_bounds__(512, 2) fwd_megakernel(Args args) {
;     extern __shared__ __attribute__((aligned(16))) unsigned char lds[];
	.amdhsa_kernel _Z14fwd_megakernel4Args
		.amdhsa_group_segment_fixed_size 0
		.amdhsa_private_segment_fixed_size 0
		.amdhsa_kernarg_size 464
		.amdhsa_user_sgpr_count 2
		.amdhsa_user_sgpr_dispatch_ptr 0
		.amdhsa_user_sgpr_queue_ptr 0
		.amdhsa_user_sgpr_kernarg_segment_ptr 1
		.amdhsa_user_sgpr_dispatch_id 0
		.amdhsa_user_sgpr_kernarg_preload_length 0
		.amdhsa_user_sgpr_kernarg_preload_offset 0
		.amdhsa_user_sgpr_private_segment_size 0
		.amdhsa_uses_dynamic_stack 0
		.amdhsa_enable_private_segment 0
		.amdhsa_system_sgpr_workgroup_id_x 1
		.amdhsa_system_sgpr_workgroup_id_y 0
		.amdhsa_system_sgpr_workgroup_id_z 0
		.amdhsa_system_sgpr_workgroup_info 0
		.amdhsa_system_vgpr_workitem_id 2
		.amdhsa_next_free_vgpr 256
		.amdhsa_next_free_sgpr 102
		.amdhsa_accum_offset 256
		.amdhsa_reserve_vcc 1
		.amdhsa_float_round_mode_32 0
		.amdhsa_float_round_mode_16_64 0
		.amdhsa_float_denorm_mode_32 3
		.amdhsa_float_denorm_mode_16_64 3
		.amdhsa_dx10_clamp 1
		.amdhsa_ieee_mode 1
		.amdhsa_fp16_overflow 0
		.amdhsa_tg_split 0
		.amdhsa_exception_fp_ieee_invalid_op 0
		.amdhsa_exception_fp_denorm_src 0
		.amdhsa_exception_fp_ieee_div_zero 0
		.amdhsa_exception_fp_ieee_overflow 0
		.amdhsa_exception_fp_ieee_underflow 0
		.amdhsa_exception_fp_ieee_inexact 0
		.amdhsa_exception_int_div_zero 0
	.end_amdhsa_kernel

; __global__ void __launch_bounds__(512, 2) fwd_megakernel(Args args) {
;     extern __shared__ __attribute__((aligned(16))) unsigned char lds[];
amdhsa.kernels:
  - .agpr_count:     0
    .args:
      - .offset:         0
        .size:           208
        .value_kind:     by_value
      - .offset:         208
        .size:           4
        .value_kind:     hidden_block_count_x
      - .offset:         212
        .size:           4
        .value_kind:     hidden_block_count_y
      - .offset:         216
        .size:           4
        .value_kind:     hidden_block_count_z
      - .offset:         220
        .size:           2
        .value_kind:     hidden_group_size_x
      - .offset:         222
        .size:           2
        .value_kind:     hidden_group_size_y
      - .offset:         224
        .size:           2
        .value_kind:     hidden_group_size_z
      - .offset:         226
        .size:           2
        .value_kind:     hidden_remainder_x
      - .offset:         228
        .size:           2
        .value_kind:     hidden_remainder_y
      - .offset:         230
        .size:           2
        .value_kind:     hidden_remainder_z
      - .offset:         248
        .size:           8
        .value_kind:     hidden_global_offset_x
      - .offset:         256
        .size:           8
        .value_kind:     hidden_global_offset_y
      - .offset:         264
        .size:           8
        .value_kind:     hidden_global_offset_z
      - .offset:         272
        .size:           2
        .value_kind:     hidden_grid_dims
      - .offset:         296
        .size:           8
        .value_kind:     hidden_multigrid_sync_arg
      - .offset:         328
        .size:           4
        .value_kind:     hidden_dynamic_lds_size
    .group_segment_fixed_size: 0
    .kernarg_segment_align: 8
    .kernarg_segment_size: 464
    .language:       OpenCL C
    .language_version:
      - 2
      - 0
    .max_flat_workgroup_size: 512
    .name:           _Z14fwd_megakernel4Args
    .private_segment_fixed_size: 0
    .sgpr_count:     108
    .sgpr_spill_count: 26
    .symbol:         _Z14fwd_megakernel4Args.kd
    .uniform_work_group_size: 1
    .uses_dynamic_stack: false
    .vgpr_count:     256
    .vgpr_spill_count: 0
    .wavefront_size: 64
